# prologue de-serialisation: attention work queue fetches the next item's index one item ahead (atomic round trip hidden behind the current item)
# baseline (speedup 1.0000x reference)
; #define LAS __attribute__((address_space(3)))
; #define LS(x) asm volatile("" : "+s"(x))
; #define PH_ENTER() int tid = tid0, blk = blk0, G = G0; unsigned long long zoff_ = 0ull; LV(tid); LS(blk); LS(G); LS(zoff_); unsigned char* ws = ws0 + zoff_; \
;         const int lane = tid & 63, wave = __builtin_amdgcn_readfirstlane(tid >> 6), gw = blk * NWAVES + wave, ngw = G * NWAVES; (void)lane; (void)gw; (void)ngw
; __device__ __forceinline__ void attn_phase(const bf16_t* FQ, const bf16_t* FK, const bf16_t* FV, const float* cum, const float* norms, bf16_t* Y, unsigned* qctr, unsigned* flags, float* parts, lptr lds, int tid_) {
;     LAS int* sh = (LAS int*)(lds + OFF_SH);
;     for (;;) {
;         int tid = tid_; asm volatile("" : "+v"(tid));
;         const int wid = __builtin_amdgcn_readfirstlane(tid >> 6), lane = tid & 63;
;         __syncthreads();
;         if (tid == 0) sh[0] = (int)__hip_atomic_fetch_add(qctr, 1u, __ATOMIC_RELAXED, __HIP_MEMORY_SCOPE_AGENT);
; template <unsigned PHMASK> __global__ void __launch_bounds__(NTHREADS, 2) fwd(Args a) {
;     ...
;             { PH_ENTER(); int l = l0; LS(l);
;               fa::attn_phase((const bf16_t*)(ws + WS_FQ), (const bf16_t*)(ws + WS_FK), (const bf16_t*)(ws + WS_FV), (const float*)(ws + WS_CUM), (const float*)(ws + WS_NORM), (bf16_t*)(ws + WS_Y),
;                              (unsigned*)(ws + WS_CTL) + CW_QUEUE + 64 * (2 * l + (rep_ & 1)), (unsigned*)(ws + WS_CTL) + CW_FLAGS + (size_t)l * 1024, (float*)(ws + WS_PART), (fa::lptr)lds, tid); }
.Lattn_prio_done:
	v_readlane_b32 s4, v254, 56
	v_readlane_b32 s5, v254, 57
	v_mov_b32_e32 v173, v0
	v_readlane_b32 s0, v254, 0
	s_load_dwordx2 s[4:5], s[4:5], 0xa0
	v_readlane_b32 s8, v254, 11
	v_readlane_b32 s0, v254, 3
	s_mov_b64 s[0:1], 0
	s_waitcnt lgkmcnt(0)
	s_add_u32 s6, s4, s0
	s_addc_u32 s7, s5, s1
	s_add_u32 s1, s6, 0x2d800000
	v_writelane_b32 v255, s1, 3
	s_addc_u32 s1, s7, 0
	v_writelane_b32 v255, s1, 4
	s_add_u32 s1, s6, 0x2f800000
	v_writelane_b32 v255, s1, 5
	s_addc_u32 s1, s7, 0
	v_writelane_b32 v255, s1, 6
	s_add_u32 s1, s6, 0x31800000
	v_writelane_b32 v255, s1, 7
	s_addc_u32 s1, s7, 0
	v_writelane_b32 v255, s1, 8
	s_add_u32 s1, s6, 0x580000
	v_writelane_b32 v255, s1, 9
	s_addc_u32 s1, s7, 0
	s_add_u32 s4, s6, 0x700000
	v_writelane_b32 v255, s1, 10
	s_addc_u32 s5, s7, 0
	v_writelane_b32 v255, s4, 11
	s_mov_b32 s0, s8
	s_add_u32 s1, s6, 0x39800000
	v_writelane_b32 v255, s5, 12
	v_writelane_b32 v255, s1, 13
	s_addc_u32 s1, s7, 0
	s_lshl_b32 s4, s0, 7
	s_ashr_i32 s5, s4, 31
	s_lshl_b64 s[4:5], s[4:5], 2
	v_writelane_b32 v255, s1, 14
	s_add_u32 s1, s6, s4
	s_addc_u32 s4, s7, s5
	v_readlane_b32 s9, v254, 12
	s_add_u32 s8, s1, 0x10000
	s_addc_u32 s9, s4, 0
	s_ashr_i32 s1, s0, 31
	s_lshl_b64 s[0:1], s[0:1], 12
	s_add_u32 s0, s6, s0
	v_writelane_b32 v255, s8, 15
	s_addc_u32 s1, s7, s1
	s_add_u32 s0, s0, 0x20000
	v_writelane_b32 v255, s9, 16
	v_writelane_b32 v255, s0, 17
	s_addc_u32 s0, s1, 0
	v_writelane_b32 v255, s0, 18
	s_add_u32 s0, s6, 0x45800000
	v_writelane_b32 v255, s0, 19
	s_addc_u32 s0, s7, 0
	v_writelane_b32 v255, s0, 20
	v_readlane_b32 s10, v254, 13
	v_readlane_b32 s11, v254, 14
	v_readlane_b32 s8, v255, 15
	v_readlane_b32 s9, v255, 16
	v_cmp_eq_u32_e64 s[4:5], 0, v0
	v_mov_b32_e32 v210, 1
	s_nop 1
	s_and_saveexec_b64 s[0:1], s[4:5]
	global_atomic_add v205, v163, v210, s[8:9] sc0
	s_or_b64 exec, exec, s[0:1]
	s_branch .LBB0_824

; __device__ __forceinline__ void attn_phase(const bf16_t* FQ, const bf16_t* FK, const bf16_t* FV, const float* cum, const float* norms, bf16_t* Y, unsigned* qctr, unsigned* flags, float* parts, lptr lds, int tid_) {
;     ...
;     for (;;) {
;         int tid = tid_; asm volatile("" : "+v"(tid));
;         const int wid = __builtin_amdgcn_readfirstlane(tid >> 6), lane = tid & 63;
;         __syncthreads();
;         if (tid == 0) sh[0] = (int)__hip_atomic_fetch_add(qctr, 1u, __ATOMIC_RELAXED, __HIP_MEMORY_SCOPE_AGENT);
;         __syncthreads();
;         const int item = sh[0];
.LBB0_824:
	v_mov_b32_e32 v174, v173
	s_waitcnt vmcnt(0)
	v_readfirstlane_b32 s12, v174
	v_cmp_eq_u32_e64 s[4:5], 0, v174
	s_barrier
	s_and_saveexec_b64 s[0:1], s[4:5]
	s_cbranch_execz .LBB0_828
	v_mov_b32_e32 v2, s62
	v_readlane_b32 s8, v255, 15
	v_readlane_b32 s9, v255, 16
	ds_write_b32 v2, v205
	s_nop 0
	s_nop 2
	global_atomic_add v205, v163, v210, s[8:9] sc0
